# layer-1 in-proj tail tiles computed by two workgroups each (K split 14/18 k-tiles, f32 accumulator hand-off through free BIG space, flag in the zeroed barrier area)
# baseline (speedup 1.0000x reference)
.LBB0_112:
	s_add_i32 s54, s54, 1
	s_mul_i32 s4, s54, s45
	s_mul_hi_u32 s5, s54, s38
	s_add_i32 s5, s5, s4
	s_mul_i32 s4, s54, s38
	s_mov_b32 s101, s2
	s_cmp_lg_u32 s54, 2
	s_cbranch_scc1 .Lp5_hdr
	s_cmpk_lg_i32 s38, 0x100
	s_cbranch_scc1 .Lp5_hdr
	s_cmp_gt_u32 s2, 63
	s_cbranch_scc1 .Lp5_hdr
	s_and_b32 s101, s2, 31
.Lp5_hdr:
	s_add_u32 s8, s4, s101
	s_addc_u32 s9, s5, s39
	v_cmp_gt_i64_e64 s[4:5], s[8:9], v[148:149]
	v_cmp_lt_i64_e64 s[6:7], s[8:9], v[146:147]
	s_and_b64 vcc, exec, s[4:5]
	s_cbranch_vccnz .LBB0_114
	s_ashr_i32 s9, s8, 31
	s_lshr_b32 s9, s9, 29
	s_add_i32 s9, s8, s9
	s_ashr_i32 s11, s9, 3
	s_and_b32 s9, s9, -8
	s_sub_i32 s8, s8, s9
	s_cmp_lt_i32 s8, 0
	s_movk_i32 s9, 0x45
	s_cselect_b32 s9, s9, 0x44
	s_mul_i32 s8, s8, s9
	s_add_i32 s8, s8, s11
	s_ashr_i32 s9, s8, 31
	s_lshr_b32 s9, s9, 25
	s_add_i32 s9, s8, s9
	s_ashr_i32 s11, s9, 7
	s_lshl_b32 s11, s11, 3
	s_sub_i32 s18, 34, s11
	s_min_i32 s18, s18, 8
	s_abs_i32 s19, s18
	v_cvt_f32_u32_e32 v0, s19
	s_sub_i32 s25, 0, s19
	s_and_b32 s9, s9, 0xffffff80
	s_sub_i32 s8, s8, s9
	v_rcp_iflag_f32_e32 v0, v0
	s_abs_i32 s9, s8
	s_xor_b32 s24, s8, s18
	s_ashr_i32 s24, s24, 31
	v_mul_f32_e32 v0, 0x4f7ffffe, v0
	v_cvt_u32_f32_e32 v0, v0
	s_nop 0
	v_readfirstlane_b32 s55, v0
	s_mul_i32 s25, s25, s55
	s_mul_hi_u32 s25, s55, s25
	s_add_i32 s55, s55, s25
	s_mul_hi_u32 s25, s9, s55
	s_mul_i32 s55, s25, s19
	s_sub_i32 s9, s9, s55
	s_add_i32 s57, s25, 1
	s_sub_i32 s55, s9, s19
	s_cmp_ge_u32 s9, s19
	s_cselect_b32 s25, s57, s25
	s_cselect_b32 s9, s55, s9
	s_add_i32 s55, s25, 1
	s_cmp_ge_u32 s9, s19
	s_cselect_b32 s9, s55, s25
	s_xor_b32 s9, s9, s24
	s_sub_i32 s55, s9, s24
	s_mul_i32 s9, s55, s18
	s_sub_i32 s8, s8, s9
	s_add_i32 s18, s11, s8

.LBB0_118:
	s_mov_b32 s100, 28
	s_cmpk_lg_i32 s38, 0x100
	s_cbranch_scc1 .Lp5_t3
	s_cmp_lg_u32 s54, 2
	s_cbranch_scc1 .Lp5_t2
	s_cmp_gt_u32 s2, 31
	s_cbranch_scc1 .Lp5_t3
	s_add_u32 s24, s24, 0x700
	s_addc_u32 s25, s25, 0
	s_add_u32 s8, s8, 0x700
	s_addc_u32 s9, s9, 0
	s_branch .Lp5_t3
.Lp5_t2:
	s_cmp_lg_u32 s54, 3
	s_cbranch_scc1 .Lp5_t3
	s_mov_b32 s100, 14
	s_bitcmp1_b32 s2, 5
	s_cbranch_scc0 .Lp5_t3
	s_mov_b32 s100, 10

.LBB0_119:
	s_add_u32 s26, s6, 0xfff80080
	s_addc_u32 s27, s7, -1
	s_add_i32 s66, 0, 0x10000
	v_add_u32_e32 v44, s66, v194
	ds_read_b128 v[24:27], v44
	ds_read_b128 v[32:35], v44 offset:1024
	ds_read_b128 v[40:43], v44 offset:2048
	ds_read_b128 v[44:47], v44 offset:3072
	s_cmp_eq_u32 s57, s100
	s_cselect_b32 s29, s25, s27
	s_cselect_b32 s28, s24, s26
	s_cselect_b32 s27, s9, s19
	s_cselect_b32 s26, s8, s11
	v_lshl_add_u64 v[180:181], s[6:7], 0, v[168:169]
	s_add_i32 m0, s36, 0xc000
	ds_read_b128 v[172:175], v196
	ds_read_b128 v[176:179], v196 offset:1024
	ds_read_b128 v[198:201], v196 offset:2048
	ds_read_b128 v[202:205], v196 offset:3072
	ds_read_b128 v[206:209], v196 offset:4096
	ds_read_b128 v[210:213], v196 offset:5120
	ds_read_b128 v[214:217], v196 offset:6144
	ds_read_b128 v[218:221], v196 offset:7168
	global_load_lds_dwordx4 v[180:181], off
	v_lshl_add_u64 v[180:181], s[6:7], 0, v[170:171]
	s_add_i32 m0, s36, 0xe000
	s_nop 0
	global_load_lds_dwordx4 v[180:181], off
	s_waitcnt lgkmcnt(8)
	s_barrier
	s_waitcnt lgkmcnt(0)
	s_setprio 1
	s_waitcnt lgkmcnt(0)
	v_mfma_f32_16x16x32_bf16 v[140:143], v[24:27], v[172:175], v[140:143]
	v_mfma_f32_16x16x32_bf16 v[136:139], v[40:43], v[172:175], v[136:139]
	v_mfma_f32_16x16x32_bf16 v[124:127], v[24:27], v[198:201], v[124:127]
	v_mfma_f32_16x16x32_bf16 v[120:123], v[40:43], v[198:201], v[120:123]
	v_mfma_f32_16x16x32_bf16 v[108:111], v[24:27], v[206:209], v[108:111]
	v_mfma_f32_16x16x32_bf16 v[104:107], v[40:43], v[206:209], v[104:107]
	v_mfma_f32_16x16x32_bf16 v[92:95], v[24:27], v[214:217], v[92:95]
	v_mfma_f32_16x16x32_bf16 v[88:91], v[40:43], v[214:217], v[88:91]
	v_mfma_f32_16x16x32_bf16 v[140:143], v[32:35], v[176:179], v[140:143]
	v_mfma_f32_16x16x32_bf16 v[136:139], v[44:47], v[176:179], v[136:139]
	v_mfma_f32_16x16x32_bf16 v[124:127], v[32:35], v[202:205], v[124:127]
	v_mfma_f32_16x16x32_bf16 v[120:123], v[44:47], v[202:205], v[120:123]
	v_mfma_f32_16x16x32_bf16 v[108:111], v[32:35], v[210:213], v[108:111]
	v_mfma_f32_16x16x32_bf16 v[104:107], v[44:47], v[210:213], v[104:107]
	v_mfma_f32_16x16x32_bf16 v[92:95], v[32:35], v[218:221], v[92:95]
	v_mfma_f32_16x16x32_bf16 v[88:91], v[44:47], v[218:221], v[88:91]
	s_setprio 0
	s_barrier
	s_add_i32 s70, 0, 0x14000
	v_add_u32_e32 v180, s70, v194
	s_add_i32 s66, s66, s35
	ds_read_b128 v[222:225], v180
	ds_read_b128 v[226:229], v180 offset:1024
	ds_read_b128 v[230:233], v180 offset:2048
	ds_read_b128 v[234:237], v180 offset:3072
	v_lshl_add_u64 v[180:181], s[26:27], 0, v[144:145]
	s_mov_b32 m0, s66
	v_lshl_add_u64 v[238:239], s[26:27], 0, v[166:167]
	global_load_lds_dwordx4 v[180:181], off
	s_add_i32 m0, s66, 0x2000
	s_nop 0
	global_load_lds_dwordx4 v[238:239], off
	s_barrier
	s_waitcnt lgkmcnt(0)
	s_setprio 1
	s_waitcnt lgkmcnt(0)
	v_mfma_f32_16x16x32_bf16 v[132:135], v[222:225], v[172:175], v[132:135]
	v_mfma_f32_16x16x32_bf16 v[128:131], v[230:233], v[172:175], v[128:131]
	v_mfma_f32_16x16x32_bf16 v[116:119], v[222:225], v[198:201], v[116:119]
	v_mfma_f32_16x16x32_bf16 v[112:115], v[230:233], v[198:201], v[112:115]
	v_mfma_f32_16x16x32_bf16 v[100:103], v[222:225], v[206:209], v[100:103]
	v_mfma_f32_16x16x32_bf16 v[96:99], v[230:233], v[206:209], v[96:99]
	v_mfma_f32_16x16x32_bf16 v[84:87], v[222:225], v[214:217], v[84:87]
	v_mfma_f32_16x16x32_bf16 v[80:83], v[230:233], v[214:217], v[80:83]
	v_mfma_f32_16x16x32_bf16 v[132:135], v[226:229], v[176:179], v[132:135]
	v_mfma_f32_16x16x32_bf16 v[128:131], v[234:237], v[176:179], v[128:131]
	v_mfma_f32_16x16x32_bf16 v[116:119], v[226:229], v[202:205], v[116:119]
	v_mfma_f32_16x16x32_bf16 v[112:115], v[234:237], v[202:205], v[112:115]
	v_mfma_f32_16x16x32_bf16 v[100:103], v[226:229], v[210:213], v[100:103]
	v_mfma_f32_16x16x32_bf16 v[96:99], v[234:237], v[210:213], v[96:99]
	v_mfma_f32_16x16x32_bf16 v[84:87], v[226:229], v[218:221], v[84:87]
	v_mfma_f32_16x16x32_bf16 v[80:83], v[234:237], v[218:221], v[80:83]
	s_setprio 0
	s_mov_b32 m0, s36
	v_lshl_add_u64 v[240:241], s[28:29], 0, v[162:163]
	s_barrier
	ds_read_b128 v[172:175], v196 offset:16384
	ds_read_b128 v[176:179], v196 offset:17408
	ds_read_b128 v[198:201], v196 offset:18432
	ds_read_b128 v[202:205], v196 offset:19456
	ds_read_b128 v[206:209], v196 offset:20480
	ds_read_b128 v[210:213], v196 offset:21504
	ds_read_b128 v[214:217], v196 offset:22528
	ds_read_b128 v[218:221], v196 offset:23552
	global_load_lds_dwordx4 v[240:241], off
	v_lshl_add_u64 v[242:243], s[28:29], 0, v[164:165]
	s_mov_b32 m0, s37
	s_nop 0
	global_load_lds_dwordx4 v[242:243], off
	s_barrier
	s_waitcnt lgkmcnt(0)
	s_setprio 1
	s_waitcnt lgkmcnt(0)
	v_mfma_f32_16x16x32_bf16 v[76:79], v[24:27], v[172:175], v[76:79]
	v_mfma_f32_16x16x32_bf16 v[72:75], v[40:43], v[172:175], v[72:75]
	v_mfma_f32_16x16x32_bf16 v[60:63], v[24:27], v[198:201], v[60:63]
	v_mfma_f32_16x16x32_bf16 v[56:59], v[40:43], v[198:201], v[56:59]
	v_mfma_f32_16x16x32_bf16 v[36:39], v[24:27], v[206:209], v[36:39]
	v_mfma_f32_16x16x32_bf16 v[28:31], v[40:43], v[206:209], v[28:31]
	v_mfma_f32_16x16x32_bf16 v[12:15], v[24:27], v[214:217], v[12:15]
	v_mfma_f32_16x16x32_bf16 v[8:11], v[40:43], v[214:217], v[8:11]
	v_mfma_f32_16x16x32_bf16 v[76:79], v[32:35], v[176:179], v[76:79]
	v_mfma_f32_16x16x32_bf16 v[72:75], v[44:47], v[176:179], v[72:75]
	v_mfma_f32_16x16x32_bf16 v[60:63], v[32:35], v[202:205], v[60:63]
	v_mfma_f32_16x16x32_bf16 v[56:59], v[44:47], v[202:205], v[56:59]
	v_mfma_f32_16x16x32_bf16 v[36:39], v[32:35], v[210:213], v[36:39]
	v_mfma_f32_16x16x32_bf16 v[28:31], v[44:47], v[210:213], v[28:31]
	v_mfma_f32_16x16x32_bf16 v[12:15], v[32:35], v[218:221], v[12:15]
	v_mfma_f32_16x16x32_bf16 v[8:11], v[44:47], v[218:221], v[8:11]
	s_setprio 0
	s_barrier
	s_add_u32 s66, s26, 0x80000
	s_addc_u32 s67, s27, 0
	s_add_i32 s70, s70, s35
	v_lshl_add_u64 v[24:25], s[66:67], 0, v[144:145]
	s_mov_b32 m0, s70
	s_nop 0
	global_load_lds_dwordx4 v[24:25], off
	v_lshl_add_u64 v[24:25], s[66:67], 0, v[166:167]
	s_add_i32 m0, s70, 0x2000
	s_nop 0
	global_load_lds_dwordx4 v[24:25], off
	s_waitcnt vmcnt(6)
	s_barrier
	s_setprio 1
	v_mfma_f32_16x16x32_bf16 v[20:23], v[222:225], v[206:209], v[20:23]
	v_mfma_f32_16x16x32_bf16 v[16:19], v[230:233], v[206:209], v[16:19]
	v_mfma_f32_16x16x32_bf16 v[4:7], v[222:225], v[214:217], v[4:7]
	v_mfma_f32_16x16x32_bf16 v[0:3], v[230:233], v[214:217], v[0:3]
	v_mfma_f32_16x16x32_bf16 v[24:27], v[222:225], v[172:175], v[68:71]
	v_mfma_f32_16x16x32_bf16 v[32:35], v[230:233], v[172:175], v[64:67]
	v_mfma_f32_16x16x32_bf16 v[40:43], v[222:225], v[198:201], v[52:55]
	v_mfma_f32_16x16x32_bf16 v[44:47], v[230:233], v[198:201], v[48:51]
	v_mfma_f32_16x16x32_bf16 v[20:23], v[226:229], v[210:213], v[20:23]
	v_mfma_f32_16x16x32_bf16 v[16:19], v[234:237], v[210:213], v[16:19]
	v_mfma_f32_16x16x32_bf16 v[4:7], v[226:229], v[218:221], v[4:7]
	v_mfma_f32_16x16x32_bf16 v[0:3], v[234:237], v[218:221], v[0:3]
	v_mfma_f32_16x16x32_bf16 v[24:27], v[226:229], v[176:179], v[24:27]
	v_mfma_f32_16x16x32_bf16 v[32:35], v[234:237], v[176:179], v[32:35]
	v_mfma_f32_16x16x32_bf16 v[40:43], v[226:229], v[202:205], v[40:43]
	v_mfma_f32_16x16x32_bf16 v[44:47], v[234:237], v[202:205], v[44:47]
	s_setprio 0
	s_add_i32 s66, 0, 0x18000
	v_add_u32_e32 v68, s66, v194
	s_barrier
	ds_read_b128 v[48:51], v68
	ds_read_b128 v[52:55], v68 offset:1024
	ds_read_b128 v[64:67], v68 offset:2048
	ds_read_b128 v[68:71], v68 offset:3072
	s_add_u32 s28, s28, 0x80000
	s_addc_u32 s29, s29, 0
	s_mov_b32 m0, s50
	v_lshl_add_u64 v[222:223], s[28:29], 0, v[162:163]
	ds_read_b128 v[172:175], v196 offset:32768
	ds_read_b128 v[176:179], v196 offset:33792
	ds_read_b128 v[198:201], v196 offset:34816
	ds_read_b128 v[202:205], v196 offset:35840
	ds_read_b128 v[206:209], v196 offset:36864
	ds_read_b128 v[210:213], v196 offset:37888
	ds_read_b128 v[214:217], v196 offset:38912
	ds_read_b128 v[218:221], v196 offset:39936
	global_load_lds_dwordx4 v[222:223], off
	v_lshl_add_u64 v[222:223], s[28:29], 0, v[164:165]
	s_mov_b32 m0, s51
	s_nop 0
	global_load_lds_dwordx4 v[222:223], off
	s_waitcnt lgkmcnt(8)
	s_barrier
	s_waitcnt lgkmcnt(0)
	s_setprio 1
	s_waitcnt lgkmcnt(0)
	v_mfma_f32_16x16x32_bf16 v[140:143], v[48:51], v[172:175], v[140:143]
	v_mfma_f32_16x16x32_bf16 v[136:139], v[64:67], v[172:175], v[136:139]
	v_mfma_f32_16x16x32_bf16 v[124:127], v[48:51], v[198:201], v[124:127]
	v_mfma_f32_16x16x32_bf16 v[120:123], v[64:67], v[198:201], v[120:123]
	v_mfma_f32_16x16x32_bf16 v[108:111], v[48:51], v[206:209], v[108:111]
	v_mfma_f32_16x16x32_bf16 v[104:107], v[64:67], v[206:209], v[104:107]
	v_mfma_f32_16x16x32_bf16 v[92:95], v[48:51], v[214:217], v[92:95]
	v_mfma_f32_16x16x32_bf16 v[88:91], v[64:67], v[214:217], v[88:91]
	v_mfma_f32_16x16x32_bf16 v[140:143], v[52:55], v[176:179], v[140:143]
	v_mfma_f32_16x16x32_bf16 v[136:139], v[68:71], v[176:179], v[136:139]
	v_mfma_f32_16x16x32_bf16 v[124:127], v[52:55], v[202:205], v[124:127]
	v_mfma_f32_16x16x32_bf16 v[120:123], v[68:71], v[202:205], v[120:123]
	v_mfma_f32_16x16x32_bf16 v[108:111], v[52:55], v[210:213], v[108:111]
	v_mfma_f32_16x16x32_bf16 v[104:107], v[68:71], v[210:213], v[104:107]
	v_mfma_f32_16x16x32_bf16 v[92:95], v[52:55], v[218:221], v[92:95]
	v_mfma_f32_16x16x32_bf16 v[88:91], v[68:71], v[218:221], v[88:91]
	s_setprio 0
	s_barrier
	s_add_i32 s28, 0, 0x1c000
	s_add_i32 s29, s66, s35
	v_add_u32_e32 v197, s28, v194
	v_lshl_add_u64 v[180:181], v[180:181], 0, s[86:87]
	s_mov_b32 m0, s29
	ds_read_b128 v[222:225], v197
	ds_read_b128 v[226:229], v197 offset:1024
	ds_read_b128 v[230:233], v197 offset:2048
	ds_read_b128 v[234:237], v197 offset:3072
	global_load_lds_dwordx4 v[180:181], off
	v_lshl_add_u64 v[180:181], v[238:239], 0, s[86:87]
	s_add_i32 m0, s29, 0x2000
	s_nop 0
	global_load_lds_dwordx4 v[180:181], off
	s_barrier
	s_waitcnt lgkmcnt(0)
	s_setprio 1
	s_waitcnt lgkmcnt(0)
	v_mfma_f32_16x16x32_bf16 v[132:135], v[222:225], v[172:175], v[132:135]
	v_mfma_f32_16x16x32_bf16 v[128:131], v[230:233], v[172:175], v[128:131]
	v_mfma_f32_16x16x32_bf16 v[116:119], v[222:225], v[198:201], v[116:119]
	v_mfma_f32_16x16x32_bf16 v[112:115], v[230:233], v[198:201], v[112:115]
	v_mfma_f32_16x16x32_bf16 v[100:103], v[222:225], v[206:209], v[100:103]
	v_mfma_f32_16x16x32_bf16 v[96:99], v[230:233], v[206:209], v[96:99]
	v_mfma_f32_16x16x32_bf16 v[84:87], v[222:225], v[214:217], v[84:87]
	v_mfma_f32_16x16x32_bf16 v[80:83], v[230:233], v[214:217], v[80:83]
	v_mfma_f32_16x16x32_bf16 v[132:135], v[226:229], v[176:179], v[132:135]
	v_mfma_f32_16x16x32_bf16 v[128:131], v[234:237], v[176:179], v[128:131]
	v_mfma_f32_16x16x32_bf16 v[116:119], v[226:229], v[202:205], v[116:119]
	v_mfma_f32_16x16x32_bf16 v[112:115], v[234:237], v[202:205], v[112:115]
	v_mfma_f32_16x16x32_bf16 v[100:103], v[226:229], v[210:213], v[100:103]
	v_mfma_f32_16x16x32_bf16 v[96:99], v[234:237], v[210:213], v[96:99]
	v_mfma_f32_16x16x32_bf16 v[84:87], v[226:229], v[218:221], v[84:87]
	v_mfma_f32_16x16x32_bf16 v[80:83], v[234:237], v[218:221], v[80:83]
	s_setprio 0
	s_mov_b32 m0, s52
	v_lshl_add_u64 v[180:181], v[240:241], 0, s[86:87]
	s_barrier
	ds_read_b128 v[172:175], v196 offset:49152
	ds_read_b128 v[176:179], v196 offset:50176
	ds_read_b128 v[198:201], v196 offset:51200
	ds_read_b128 v[202:205], v196 offset:52224
	ds_read_b128 v[206:209], v196 offset:53248
	ds_read_b128 v[210:213], v196 offset:54272
	ds_read_b128 v[214:217], v196 offset:55296
	ds_read_b128 v[218:221], v196 offset:56320
	global_load_lds_dwordx4 v[180:181], off
	v_lshl_add_u64 v[180:181], v[242:243], 0, s[86:87]
	s_mov_b32 m0, s53
	s_nop 0
	global_load_lds_dwordx4 v[180:181], off
	s_barrier
	s_waitcnt lgkmcnt(0)
	s_setprio 1
	s_waitcnt lgkmcnt(0)
	v_mfma_f32_16x16x32_bf16 v[76:79], v[48:51], v[172:175], v[76:79]
	v_mfma_f32_16x16x32_bf16 v[72:75], v[64:67], v[172:175], v[72:75]
	v_mfma_f32_16x16x32_bf16 v[60:63], v[48:51], v[198:201], v[60:63]
	v_mfma_f32_16x16x32_bf16 v[56:59], v[64:67], v[198:201], v[56:59]
	v_mfma_f32_16x16x32_bf16 v[36:39], v[48:51], v[206:209], v[36:39]
	v_mfma_f32_16x16x32_bf16 v[28:31], v[64:67], v[206:209], v[28:31]
	v_mfma_f32_16x16x32_bf16 v[12:15], v[48:51], v[214:217], v[12:15]
	v_mfma_f32_16x16x32_bf16 v[8:11], v[64:67], v[214:217], v[8:11]
	v_mfma_f32_16x16x32_bf16 v[76:79], v[52:55], v[176:179], v[76:79]
	v_mfma_f32_16x16x32_bf16 v[72:75], v[68:71], v[176:179], v[72:75]
	v_mfma_f32_16x16x32_bf16 v[60:63], v[52:55], v[202:205], v[60:63]
	v_mfma_f32_16x16x32_bf16 v[56:59], v[68:71], v[202:205], v[56:59]
	v_mfma_f32_16x16x32_bf16 v[36:39], v[52:55], v[210:213], v[36:39]
	v_mfma_f32_16x16x32_bf16 v[28:31], v[68:71], v[210:213], v[28:31]
	v_mfma_f32_16x16x32_bf16 v[12:15], v[52:55], v[218:221], v[12:15]
	v_mfma_f32_16x16x32_bf16 v[8:11], v[68:71], v[218:221], v[8:11]
	s_setprio 0
	s_barrier
	s_add_u32 s26, s26, 0x80080
	s_addc_u32 s27, s27, 0
	s_add_i32 s28, s28, s35
	v_lshl_add_u64 v[48:49], s[26:27], 0, v[144:145]
	s_mov_b32 m0, s28
	s_nop 0
	global_load_lds_dwordx4 v[48:49], off
	v_lshl_add_u64 v[48:49], s[26:27], 0, v[166:167]
	s_add_i32 m0, s28, 0x2000
	s_nop 0
	global_load_lds_dwordx4 v[48:49], off
	s_waitcnt vmcnt(6)
	s_barrier
	s_setprio 1
	v_mfma_f32_16x16x32_bf16 v[24:27], v[222:225], v[172:175], v[24:27]
	v_mfma_f32_16x16x32_bf16 v[68:71], v[226:229], v[176:179], v[24:27]
	v_mfma_f32_16x16x32_bf16 v[24:27], v[230:233], v[172:175], v[32:35]
	v_mfma_f32_16x16x32_bf16 v[64:67], v[234:237], v[176:179], v[24:27]
	v_mfma_f32_16x16x32_bf16 v[24:27], v[222:225], v[198:201], v[40:43]
	v_mfma_f32_16x16x32_bf16 v[52:55], v[226:229], v[202:205], v[24:27]
	v_mfma_f32_16x16x32_bf16 v[24:27], v[230:233], v[198:201], v[44:47]
	v_mfma_f32_16x16x32_bf16 v[20:23], v[222:225], v[206:209], v[20:23]
	v_mfma_f32_16x16x32_bf16 v[16:19], v[230:233], v[206:209], v[16:19]
	v_mfma_f32_16x16x32_bf16 v[4:7], v[222:225], v[214:217], v[4:7]
	v_mfma_f32_16x16x32_bf16 v[0:3], v[230:233], v[214:217], v[0:3]
	v_mfma_f32_16x16x32_bf16 v[48:51], v[234:237], v[202:205], v[24:27]
	v_mfma_f32_16x16x32_bf16 v[20:23], v[226:229], v[210:213], v[20:23]
	v_mfma_f32_16x16x32_bf16 v[16:19], v[234:237], v[210:213], v[16:19]
	v_mfma_f32_16x16x32_bf16 v[4:7], v[226:229], v[218:221], v[4:7]
	v_mfma_f32_16x16x32_bf16 v[0:3], v[234:237], v[218:221], v[0:3]
	s_setprio 0
	s_add_i32 s57, s57, 2
	s_add_u32 s6, s6, 0x100
	s_addc_u32 s7, s7, 0
	s_add_u32 s11, s11, 0x100
	s_addc_u32 s19, s19, 0
	s_cmp_gt_u32 s57, s100
	s_barrier
	s_cbranch_scc0 .LBB0_119
	s_cmp_lg_u32 s54, 3
	s_cbranch_scc1 .Lp5_noex
	s_cmpk_lg_i32 s38, 0x100
	s_cbranch_scc1 .Lp5_noex
	s_load_dwordx2 s[100:101], s[20:21], 0xa8
	v_and_b32_e32 v230, 63, v182
	v_lshlrev_b32_e32 v230, 4, v230
	v_lshrrev_b32_e32 v231, 6, v182
	v_lshl_add_u32 v230, v231, 15, v230
	s_and_b32 vcc_lo, s2, 31
	s_lshl_b32 vcc_hi, vcc_lo, 2
	s_add_u32 vcc_hi, vcc_hi, 0x1aba0000
	v_mov_b32_e32 v234, vcc_hi
	v_mov_b32_e32 v235, 0
	s_lshl_b32 vcc_lo, vcc_lo, 18
	s_add_u32 vcc_lo, vcc_lo, 0x12200000
	s_waitcnt lgkmcnt(0)
	v_lshl_add_u64 v[232:233], s[100:101], 0, v[234:235]
	s_add_u32 s100, s100, vcc_lo
	s_addc_u32 s101, s101, 0
	s_bitcmp1_b32 s2, 5
	s_cbranch_scc0 .Lp5_red
	global_store_dwordx4 v230, v[0:3], s[100:101] sc0 sc1
	s_add_u32 s100, s100, 0x400
	s_addc_u32 s101, s101, 0
	global_store_dwordx4 v230, v[4:7], s[100:101] sc0 sc1
	s_add_u32 s100, s100, 0x400
	s_addc_u32 s101, s101, 0
	global_store_dwordx4 v230, v[8:11], s[100:101] sc0 sc1
	s_add_u32 s100, s100, 0x400
	s_addc_u32 s101, s101, 0
	global_store_dwordx4 v230, v[12:15], s[100:101] sc0 sc1
	s_add_u32 s100, s100, 0x400
	s_addc_u32 s101, s101, 0
	global_store_dwordx4 v230, v[16:19], s[100:101] sc0 sc1
	s_add_u32 s100, s100, 0x400
	s_addc_u32 s101, s101, 0
	global_store_dwordx4 v230, v[20:23], s[100:101] sc0 sc1
	s_add_u32 s100, s100, 0x400
	s_addc_u32 s101, s101, 0
	global_store_dwordx4 v230, v[28:31], s[100:101] sc0 sc1
	s_add_u32 s100, s100, 0x400
	s_addc_u32 s101, s101, 0
	global_store_dwordx4 v230, v[36:39], s[100:101] sc0 sc1
	s_add_u32 s100, s100, 0x400
	s_addc_u32 s101, s101, 0
	global_store_dwordx4 v230, v[48:51], s[100:101] sc0 sc1
	s_add_u32 s100, s100, 0x400
	s_addc_u32 s101, s101, 0
	global_store_dwordx4 v230, v[52:55], s[100:101] sc0 sc1
	s_add_u32 s100, s100, 0x400
	s_addc_u32 s101, s101, 0
	global_store_dwordx4 v230, v[56:59], s[100:101] sc0 sc1
	s_add_u32 s100, s100, 0x400
	s_addc_u32 s101, s101, 0
	global_store_dwordx4 v230, v[60:63], s[100:101] sc0 sc1
	s_add_u32 s100, s100, 0x400
	s_addc_u32 s101, s101, 0
	global_store_dwordx4 v230, v[64:67], s[100:101] sc0 sc1
	s_add_u32 s100, s100, 0x400
	s_addc_u32 s101, s101, 0
	global_store_dwordx4 v230, v[68:71], s[100:101] sc0 sc1
	s_add_u32 s100, s100, 0x400
	s_addc_u32 s101, s101, 0
	global_store_dwordx4 v230, v[72:75], s[100:101] sc0 sc1
	s_add_u32 s100, s100, 0x400
	s_addc_u32 s101, s101, 0
	global_store_dwordx4 v230, v[76:79], s[100:101] sc0 sc1
	s_add_u32 s100, s100, 0x400
	s_addc_u32 s101, s101, 0
	global_store_dwordx4 v230, v[80:83], s[100:101] sc0 sc1
	s_add_u32 s100, s100, 0x400
	s_addc_u32 s101, s101, 0
	global_store_dwordx4 v230, v[84:87], s[100:101] sc0 sc1
	s_add_u32 s100, s100, 0x400
	s_addc_u32 s101, s101, 0
	global_store_dwordx4 v230, v[88:91], s[100:101] sc0 sc1
	s_add_u32 s100, s100, 0x400
	s_addc_u32 s101, s101, 0
	global_store_dwordx4 v230, v[92:95], s[100:101] sc0 sc1
	s_add_u32 s100, s100, 0x400
	s_addc_u32 s101, s101, 0
	global_store_dwordx4 v230, v[96:99], s[100:101] sc0 sc1
	s_add_u32 s100, s100, 0x400
	s_addc_u32 s101, s101, 0
	global_store_dwordx4 v230, v[100:103], s[100:101] sc0 sc1
	s_add_u32 s100, s100, 0x400
	s_addc_u32 s101, s101, 0
	global_store_dwordx4 v230, v[104:107], s[100:101] sc0 sc1
	s_add_u32 s100, s100, 0x400
	s_addc_u32 s101, s101, 0
	global_store_dwordx4 v230, v[108:111], s[100:101] sc0 sc1
	s_add_u32 s100, s100, 0x400
	s_addc_u32 s101, s101, 0
	global_store_dwordx4 v230, v[112:115], s[100:101] sc0 sc1
	s_add_u32 s100, s100, 0x400
	s_addc_u32 s101, s101, 0
	global_store_dwordx4 v230, v[116:119], s[100:101] sc0 sc1
	s_add_u32 s100, s100, 0x400
	s_addc_u32 s101, s101, 0
	global_store_dwordx4 v230, v[120:123], s[100:101] sc0 sc1
	s_add_u32 s100, s100, 0x400
	s_addc_u32 s101, s101, 0
	global_store_dwordx4 v230, v[124:127], s[100:101] sc0 sc1
	s_add_u32 s100, s100, 0x400
	s_addc_u32 s101, s101, 0
	global_store_dwordx4 v230, v[128:131], s[100:101] sc0 sc1
	s_add_u32 s100, s100, 0x400
	s_addc_u32 s101, s101, 0
	global_store_dwordx4 v230, v[132:135], s[100:101] sc0 sc1
	s_add_u32 s100, s100, 0x400
	s_addc_u32 s101, s101, 0
	global_store_dwordx4 v230, v[136:139], s[100:101] sc0 sc1
	s_add_u32 s100, s100, 0x400
	s_addc_u32 s101, s101, 0
	global_store_dwordx4 v230, v[140:143], s[100:101] sc0 sc1
	s_add_u32 s100, s100, 0x400
	s_addc_u32 s101, s101, 0
	s_waitcnt vmcnt(0)
	s_barrier
	v_cmp_eq_u32_e32 vcc, 0, v182
	s_and_saveexec_b64 s[100:101], vcc
	v_mov_b32_e32 v231, 1
	global_store_dword v[232:233], v231, off sc0 sc1
	s_mov_b64 exec, s[100:101]
	s_branch .LBB0_151
.Lp5_red:
	v_mov_b32_e32 v231, 0
.Lp5_poll:
	global_load_dword v234, v[232:233], off sc0 sc1
	s_waitcnt vmcnt(0)
	v_cmp_eq_u32_e32 vcc, 1, v234
	s_cbranch_vccnz .Lp5_got
	s_sleep 2
	v_add_u32_e32 v231, 1, v231
	v_cmp_gt_u32_e32 vcc, 0x20000, v231
	s_cbranch_vccnz .Lp5_poll
.Lp5_got:
	global_load_dwordx4 v[198:201], v230, s[100:101] sc0 sc1
	s_add_u32 s100, s100, 0x400
	s_addc_u32 s101, s101, 0
	global_load_dwordx4 v[202:205], v230, s[100:101] sc0 sc1
	s_add_u32 s100, s100, 0x400
	s_addc_u32 s101, s101, 0
	global_load_dwordx4 v[206:209], v230, s[100:101] sc0 sc1
	s_add_u32 s100, s100, 0x400
	s_addc_u32 s101, s101, 0
	global_load_dwordx4 v[210:213], v230, s[100:101] sc0 sc1
	s_add_u32 s100, s100, 0x400
	s_addc_u32 s101, s101, 0
	global_load_dwordx4 v[214:217], v230, s[100:101] sc0 sc1
	s_add_u32 s100, s100, 0x400
	s_addc_u32 s101, s101, 0
	global_load_dwordx4 v[218:221], v230, s[100:101] sc0 sc1
	s_add_u32 s100, s100, 0x400
	s_addc_u32 s101, s101, 0
	global_load_dwordx4 v[222:225], v230, s[100:101] sc0 sc1
	s_add_u32 s100, s100, 0x400
	s_addc_u32 s101, s101, 0
	global_load_dwordx4 v[226:229], v230, s[100:101] sc0 sc1
	s_add_u32 s100, s100, 0x400
	s_addc_u32 s101, s101, 0
	s_waitcnt vmcnt(0)
	v_pk_add_f32 v[0:1], v[0:1], v[198:199]
	v_pk_add_f32 v[2:3], v[2:3], v[200:201]
	v_pk_add_f32 v[4:5], v[4:5], v[202:203]
	v_pk_add_f32 v[6:7], v[6:7], v[204:205]
	v_pk_add_f32 v[8:9], v[8:9], v[206:207]
	v_pk_add_f32 v[10:11], v[10:11], v[208:209]
	v_pk_add_f32 v[12:13], v[12:13], v[210:211]
	v_pk_add_f32 v[14:15], v[14:15], v[212:213]
	v_pk_add_f32 v[16:17], v[16:17], v[214:215]
	v_pk_add_f32 v[18:19], v[18:19], v[216:217]
	v_pk_add_f32 v[20:21], v[20:21], v[218:219]
	v_pk_add_f32 v[22:23], v[22:23], v[220:221]
	v_pk_add_f32 v[28:29], v[28:29], v[222:223]
	v_pk_add_f32 v[30:31], v[30:31], v[224:225]
	v_pk_add_f32 v[36:37], v[36:37], v[226:227]
	v_pk_add_f32 v[38:39], v[38:39], v[228:229]
	global_load_dwordx4 v[198:201], v230, s[100:101] sc0 sc1
	s_add_u32 s100, s100, 0x400
	s_addc_u32 s101, s101, 0
	global_load_dwordx4 v[202:205], v230, s[100:101] sc0 sc1
	s_add_u32 s100, s100, 0x400
	s_addc_u32 s101, s101, 0
	global_load_dwordx4 v[206:209], v230, s[100:101] sc0 sc1
	s_add_u32 s100, s100, 0x400
	s_addc_u32 s101, s101, 0
	global_load_dwordx4 v[210:213], v230, s[100:101] sc0 sc1
	s_add_u32 s100, s100, 0x400
	s_addc_u32 s101, s101, 0
	global_load_dwordx4 v[214:217], v230, s[100:101] sc0 sc1
	s_add_u32 s100, s100, 0x400
	s_addc_u32 s101, s101, 0
	global_load_dwordx4 v[218:221], v230, s[100:101] sc0 sc1
	s_add_u32 s100, s100, 0x400
	s_addc_u32 s101, s101, 0
	global_load_dwordx4 v[222:225], v230, s[100:101] sc0 sc1
	s_add_u32 s100, s100, 0x400
	s_addc_u32 s101, s101, 0
	global_load_dwordx4 v[226:229], v230, s[100:101] sc0 sc1
	s_add_u32 s100, s100, 0x400
	s_addc_u32 s101, s101, 0
	s_waitcnt vmcnt(0)
	v_pk_add_f32 v[48:49], v[48:49], v[198:199]
	v_pk_add_f32 v[50:51], v[50:51], v[200:201]
	v_pk_add_f32 v[52:53], v[52:53], v[202:203]
	v_pk_add_f32 v[54:55], v[54:55], v[204:205]
	v_pk_add_f32 v[56:57], v[56:57], v[206:207]
	v_pk_add_f32 v[58:59], v[58:59], v[208:209]
	v_pk_add_f32 v[60:61], v[60:61], v[210:211]
	v_pk_add_f32 v[62:63], v[62:63], v[212:213]
	v_pk_add_f32 v[64:65], v[64:65], v[214:215]
	v_pk_add_f32 v[66:67], v[66:67], v[216:217]
	v_pk_add_f32 v[68:69], v[68:69], v[218:219]
	v_pk_add_f32 v[70:71], v[70:71], v[220:221]
	v_pk_add_f32 v[72:73], v[72:73], v[222:223]
	v_pk_add_f32 v[74:75], v[74:75], v[224:225]
	v_pk_add_f32 v[76:77], v[76:77], v[226:227]
	v_pk_add_f32 v[78:79], v[78:79], v[228:229]
	global_load_dwordx4 v[198:201], v230, s[100:101] sc0 sc1
	s_add_u32 s100, s100, 0x400
	s_addc_u32 s101, s101, 0
	global_load_dwordx4 v[202:205], v230, s[100:101] sc0 sc1
	s_add_u32 s100, s100, 0x400
	s_addc_u32 s101, s101, 0
	global_load_dwordx4 v[206:209], v230, s[100:101] sc0 sc1
	s_add_u32 s100, s100, 0x400
	s_addc_u32 s101, s101, 0
	global_load_dwordx4 v[210:213], v230, s[100:101] sc0 sc1
	s_add_u32 s100, s100, 0x400
	s_addc_u32 s101, s101, 0
	global_load_dwordx4 v[214:217], v230, s[100:101] sc0 sc1
	s_add_u32 s100, s100, 0x400
	s_addc_u32 s101, s101, 0
	global_load_dwordx4 v[218:221], v230, s[100:101] sc0 sc1
	s_add_u32 s100, s100, 0x400
	s_addc_u32 s101, s101, 0
	global_load_dwordx4 v[222:225], v230, s[100:101] sc0 sc1
	s_add_u32 s100, s100, 0x400
	s_addc_u32 s101, s101, 0
	global_load_dwordx4 v[226:229], v230, s[100:101] sc0 sc1
	s_add_u32 s100, s100, 0x400
	s_addc_u32 s101, s101, 0
	s_waitcnt vmcnt(0)
	v_pk_add_f32 v[80:81], v[80:81], v[198:199]
	v_pk_add_f32 v[82:83], v[82:83], v[200:201]
	v_pk_add_f32 v[84:85], v[84:85], v[202:203]
	v_pk_add_f32 v[86:87], v[86:87], v[204:205]
	v_pk_add_f32 v[88:89], v[88:89], v[206:207]
	v_pk_add_f32 v[90:91], v[90:91], v[208:209]
	v_pk_add_f32 v[92:93], v[92:93], v[210:211]
	v_pk_add_f32 v[94:95], v[94:95], v[212:213]
	v_pk_add_f32 v[96:97], v[96:97], v[214:215]
	v_pk_add_f32 v[98:99], v[98:99], v[216:217]
	v_pk_add_f32 v[100:101], v[100:101], v[218:219]
	v_pk_add_f32 v[102:103], v[102:103], v[220:221]
	v_pk_add_f32 v[104:105], v[104:105], v[222:223]
	v_pk_add_f32 v[106:107], v[106:107], v[224:225]
	v_pk_add_f32 v[108:109], v[108:109], v[226:227]
	v_pk_add_f32 v[110:111], v[110:111], v[228:229]
	global_load_dwordx4 v[198:201], v230, s[100:101] sc0 sc1
	s_add_u32 s100, s100, 0x400
	s_addc_u32 s101, s101, 0
	global_load_dwordx4 v[202:205], v230, s[100:101] sc0 sc1
	s_add_u32 s100, s100, 0x400
	s_addc_u32 s101, s101, 0
	global_load_dwordx4 v[206:209], v230, s[100:101] sc0 sc1
	s_add_u32 s100, s100, 0x400
	s_addc_u32 s101, s101, 0
	global_load_dwordx4 v[210:213], v230, s[100:101] sc0 sc1
	s_add_u32 s100, s100, 0x400
	s_addc_u32 s101, s101, 0
	global_load_dwordx4 v[214:217], v230, s[100:101] sc0 sc1
	s_add_u32 s100, s100, 0x400
	s_addc_u32 s101, s101, 0
	global_load_dwordx4 v[218:221], v230, s[100:101] sc0 sc1
	s_add_u32 s100, s100, 0x400
	s_addc_u32 s101, s101, 0
	global_load_dwordx4 v[222:225], v230, s[100:101] sc0 sc1
	s_add_u32 s100, s100, 0x400
	s_addc_u32 s101, s101, 0
	global_load_dwordx4 v[226:229], v230, s[100:101] sc0 sc1
	s_add_u32 s100, s100, 0x400
	s_addc_u32 s101, s101, 0
	s_waitcnt vmcnt(0)
	v_pk_add_f32 v[112:113], v[112:113], v[198:199]
	v_pk_add_f32 v[114:115], v[114:115], v[200:201]
	v_pk_add_f32 v[116:117], v[116:117], v[202:203]
	v_pk_add_f32 v[118:119], v[118:119], v[204:205]
	v_pk_add_f32 v[120:121], v[120:121], v[206:207]
	v_pk_add_f32 v[122:123], v[122:123], v[208:209]
	v_pk_add_f32 v[124:125], v[124:125], v[210:211]
	v_pk_add_f32 v[126:127], v[126:127], v[212:213]
	v_pk_add_f32 v[128:129], v[128:129], v[214:215]
	v_pk_add_f32 v[130:131], v[130:131], v[216:217]
	v_pk_add_f32 v[132:133], v[132:133], v[218:219]
	v_pk_add_f32 v[134:135], v[134:135], v[220:221]
	v_pk_add_f32 v[136:137], v[136:137], v[222:223]
	v_pk_add_f32 v[138:139], v[138:139], v[224:225]
	v_pk_add_f32 v[140:141], v[140:141], v[226:227]
	v_pk_add_f32 v[142:143], v[142:143], v[228:229]
.Lp5_noex:
	s_load_dwordx2 s[6:7], s[20:21], 0x58
	v_lshl_or_b32 v172, s56, 8, v195
	v_ashrrev_i32_e32 v173, 31, v172
	s_cmp_gt_i32 s56, 7
	v_lshl_add_u32 v174, s10, 8, v193
	s_waitcnt lgkmcnt(0)
	v_lshl_add_u64 v[32:33], v[172:173], 2, s[6:7]
	global_load_dwordx4 v[40:43], v[32:33], off offset:16
	global_load_dwordx4 v[44:47], v[32:33], off
	global_load_dwordx4 v[24:27], v[32:33], off offset:528
	s_nop 0
	global_load_dwordx4 v[32:35], v[32:33], off offset:512
	s_cselect_b64 s[10:11], -1, 0
	s_lshl_b32 s6, s56, 2
	s_sub_i32 s6, s6, 32
	s_ashr_i32 s7, s6, 31
	s_or_b64 s[26:27], s[6:7], s[76:77]
	s_mov_b32 s6, 0x3e6d3388
	s_mov_b32 s28, 0xbf3a00e3
	v_ashrrev_i32_e32 v175, 31, v174
	v_lshlrev_b64 v[176:177], 13, v[174:175]
	v_lshl_add_u64 v[176:177], s[14:15], 0, v[176:177]
	v_lshl_add_u64 v[176:177], v[172:173], 1, v[176:177]
	s_cmp_lt_i32 s56, 8
	s_waitcnt vmcnt(0)
	v_pk_add_f32 v[136:137], v[136:137], v[40:41]
	v_pk_add_f32 v[140:141], v[140:141], v[44:45]
	v_pk_add_f32 v[142:143], v[142:143], v[46:47]
	v_and_b32_e32 v181, 0x7fffffff, v141
	v_and_b32_e32 v180, 0x7fffffff, v140
	v_pk_fma_f32 v[178:179], v[180:181], s[6:7], 1.0 op_sel_hi:[1,0,0]
	v_pk_mul_f32 v[202:203], v[140:141], v[140:141]
	v_rcp_f32_e32 v198, v178
	v_rcp_f32_e32 v199, v179
	v_mov_b64_e32 v[178:179], s[28:29]
	v_pk_mul_f32 v[202:203], v[202:203], s[60:61] op_sel_hi:[1,0]
	v_pk_add_f32 v[138:139], v[138:139], v[42:43]
	v_pk_fma_f32 v[200:201], v[198:199], s[92:93], v[178:179] op_sel_hi:[1,0,0]
	v_exp_f32_e32 v202, v202
	v_pk_fma_f32 v[200:201], v[198:199], v[200:201], s[96:97] op_sel_hi:[1,1,0]
	v_exp_f32_e32 v203, v203
	v_pk_fma_f32 v[200:201], v[198:199], v[200:201], s[44:45] op_sel_hi:[1,1,0]
	v_pk_add_f32 v[132:133], v[132:133], v[32:33]
	v_pk_fma_f32 v[200:201], v[198:199], v[200:201], s[58:59] op_sel_hi:[1,1,0]
	v_pk_add_f32 v[134:135], v[134:135], v[34:35]
	v_pk_mul_f32 v[198:199], v[198:199], v[200:201]
	v_pk_mul_f32 v[200:201], v[142:143], v[142:143]
	v_pk_fma_f32 v[198:199], v[202:203], v[198:199], 0.5 op_sel_hi:[1,1,0] neg_lo:[1,0,0] neg_hi:[1,0,0]
	v_pk_mul_f32 v[200:201], v[200:201], s[60:61] op_sel_hi:[1,0]
	v_pk_mul_f32 v[180:181], v[180:181], v[198:199]
	v_exp_f32_e32 v200, v200
	v_pk_fma_f32 v[140:141], v[140:141], 0.5, v[180:181] op_sel_hi:[1,0,1]
	v_and_b32_e32 v181, 0x7fffffff, v143
	v_and_b32_e32 v180, 0x7fffffff, v142
	v_pk_fma_f32 v[198:199], v[180:181], s[6:7], 1.0 op_sel_hi:[1,0,0]
	v_exp_f32_e32 v201, v201
	v_rcp_f32_e32 v198, v198
	v_rcp_f32_e32 v199, v199
	v_pk_add_f32 v[128:129], v[128:129], v[24:25]
	v_pk_add_f32 v[130:131], v[130:131], v[26:27]
	v_pk_fma_f32 v[202:203], v[198:199], s[92:93], v[178:179] op_sel_hi:[1,0,0]
	s_nop 0
	v_pk_fma_f32 v[202:203], v[198:199], v[202:203], s[96:97] op_sel_hi:[1,1,0]
	s_nop 0
	v_pk_fma_f32 v[202:203], v[198:199], v[202:203], s[44:45] op_sel_hi:[1,1,0]
	s_nop 0
	v_pk_fma_f32 v[202:203], v[198:199], v[202:203], s[58:59] op_sel_hi:[1,1,0]
	s_nop 0
	v_pk_mul_f32 v[198:199], v[198:199], v[202:203]
	v_pk_mul_f32 v[202:203], v[136:137], v[136:137]
	v_pk_fma_f32 v[198:199], v[200:201], v[198:199], 0.5 op_sel_hi:[1,1,0] neg_lo:[1,0,0] neg_hi:[1,0,0]
	v_pk_mul_f32 v[202:203], v[202:203], s[60:61] op_sel_hi:[1,0]
	v_pk_mul_f32 v[180:181], v[180:181], v[198:199]
	v_exp_f32_e32 v202, v202
	v_pk_fma_f32 v[142:143], v[142:143], 0.5, v[180:181] op_sel_hi:[1,0,1]
	v_and_b32_e32 v181, 0x7fffffff, v137
	v_and_b32_e32 v180, 0x7fffffff, v136
	v_pk_fma_f32 v[198:199], v[180:181], s[6:7], 1.0 op_sel_hi:[1,0,0]
	v_exp_f32_e32 v203, v203
	v_rcp_f32_e32 v198, v198
	v_rcp_f32_e32 v199, v199
	s_nop 0
	v_pk_fma_f32 v[200:201], v[198:199], s[92:93], v[178:179] op_sel_hi:[1,0,0]
	s_nop 0
	v_pk_fma_f32 v[200:201], v[198:199], v[200:201], s[96:97] op_sel_hi:[1,1,0]
	s_nop 0
	v_pk_fma_f32 v[200:201], v[198:199], v[200:201], s[44:45] op_sel_hi:[1,1,0]
	s_nop 0
	v_pk_fma_f32 v[200:201], v[198:199], v[200:201], s[58:59] op_sel_hi:[1,1,0]
	s_nop 0
	v_pk_mul_f32 v[198:199], v[198:199], v[200:201]
	v_pk_mul_f32 v[200:201], v[138:139], v[138:139]
	v_pk_fma_f32 v[198:199], v[202:203], v[198:199], 0.5 op_sel_hi:[1,1,0] neg_lo:[1,0,0] neg_hi:[1,0,0]
	v_pk_mul_f32 v[200:201], v[200:201], s[60:61] op_sel_hi:[1,0]
	v_pk_mul_f32 v[180:181], v[180:181], v[198:199]
	v_exp_f32_e32 v200, v200
	v_pk_fma_f32 v[136:137], v[136:137], 0.5, v[180:181] op_sel_hi:[1,0,1]
	v_and_b32_e32 v181, 0x7fffffff, v139
	v_and_b32_e32 v180, 0x7fffffff, v138
	v_pk_fma_f32 v[198:199], v[180:181], s[6:7], 1.0 op_sel_hi:[1,0,0]
	v_exp_f32_e32 v201, v201
	v_rcp_f32_e32 v198, v198
	v_rcp_f32_e32 v199, v199
	s_nop 0
	v_pk_fma_f32 v[202:203], v[198:199], s[92:93], v[178:179] op_sel_hi:[1,0,0]
	s_nop 0
	v_pk_fma_f32 v[202:203], v[198:199], v[202:203], s[96:97] op_sel_hi:[1,1,0]
	s_nop 0
	v_pk_fma_f32 v[202:203], v[198:199], v[202:203], s[44:45] op_sel_hi:[1,1,0]
	s_nop 0
	v_pk_fma_f32 v[202:203], v[198:199], v[202:203], s[58:59] op_sel_hi:[1,1,0]
	s_nop 0
	v_pk_mul_f32 v[198:199], v[198:199], v[202:203]
	v_pk_mul_f32 v[202:203], v[132:133], v[132:133]
	v_pk_fma_f32 v[198:199], v[200:201], v[198:199], 0.5 op_sel_hi:[1,1,0] neg_lo:[1,0,0] neg_hi:[1,0,0]
	v_cvt_pk_bf16_f32 v200, v136, v137
	v_pk_mul_f32 v[202:203], v[202:203], s[60:61] op_sel_hi:[1,0]
	v_pk_mul_f32 v[180:181], v[180:181], v[198:199]
	v_cvt_pk_bf16_f32 v198, v140, v141
	v_cvt_pk_bf16_f32 v199, v142, v143
	v_exp_f32_e32 v202, v202
	v_pk_fma_f32 v[138:139], v[138:139], 0.5, v[180:181] op_sel_hi:[1,0,1]
	v_and_b32_e32 v181, 0x7fffffff, v133
	v_and_b32_e32 v180, 0x7fffffff, v132
	v_cvt_pk_bf16_f32 v201, v138, v139
	global_store_dwordx4 v[176:177], v[198:201], off
	v_exp_f32_e32 v203, v203
	s_nop 0
	v_pk_fma_f32 v[198:199], v[180:181], s[6:7], 1.0 op_sel_hi:[1,0,0]
	s_nop 0
	v_rcp_f32_e32 v198, v198
	v_rcp_f32_e32 v199, v199
	s_nop 0
	v_pk_fma_f32 v[200:201], v[198:199], s[92:93], v[178:179] op_sel_hi:[1,0,0]
	s_nop 0
	v_pk_fma_f32 v[200:201], v[198:199], v[200:201], s[96:97] op_sel_hi:[1,1,0]
	s_nop 0
	v_pk_fma_f32 v[200:201], v[198:199], v[200:201], s[44:45] op_sel_hi:[1,1,0]
	s_nop 0
	v_pk_fma_f32 v[200:201], v[198:199], v[200:201], s[58:59] op_sel_hi:[1,1,0]
	s_nop 0
	v_pk_mul_f32 v[198:199], v[198:199], v[200:201]
	v_pk_mul_f32 v[200:201], v[134:135], v[134:135]
	v_pk_fma_f32 v[198:199], v[202:203], v[198:199], 0.5 op_sel_hi:[1,1,0] neg_lo:[1,0,0] neg_hi:[1,0,0]
	v_pk_mul_f32 v[200:201], v[200:201], s[60:61] op_sel_hi:[1,0]
	v_pk_mul_f32 v[180:181], v[180:181], v[198:199]
	v_exp_f32_e32 v200, v200
	v_pk_fma_f32 v[132:133], v[132:133], 0.5, v[180:181] op_sel_hi:[1,0,1]
	v_and_b32_e32 v181, 0x7fffffff, v135
	v_and_b32_e32 v180, 0x7fffffff, v134
	v_pk_fma_f32 v[198:199], v[180:181], s[6:7], 1.0 op_sel_hi:[1,0,0]
	v_exp_f32_e32 v201, v201
	v_rcp_f32_e32 v198, v198
	v_rcp_f32_e32 v199, v199
	s_nop 0
	v_pk_fma_f32 v[202:203], v[198:199], s[92:93], v[178:179] op_sel_hi:[1,0,0]
	s_nop 0
	v_pk_fma_f32 v[202:203], v[198:199], v[202:203], s[96:97] op_sel_hi:[1,1,0]
	s_nop 0
	v_pk_fma_f32 v[202:203], v[198:199], v[202:203], s[44:45] op_sel_hi:[1,1,0]
	s_nop 0
	v_pk_fma_f32 v[202:203], v[198:199], v[202:203], s[58:59] op_sel_hi:[1,1,0]
	s_nop 0
	v_pk_mul_f32 v[198:199], v[198:199], v[202:203]
	v_pk_mul_f32 v[202:203], v[128:129], v[128:129]
	v_pk_fma_f32 v[198:199], v[200:201], v[198:199], 0.5 op_sel_hi:[1,1,0] neg_lo:[1,0,0] neg_hi:[1,0,0]
	v_pk_mul_f32 v[202:203], v[202:203], s[60:61] op_sel_hi:[1,0]
	v_pk_mul_f32 v[180:181], v[180:181], v[198:199]
	v_exp_f32_e32 v202, v202
	v_pk_fma_f32 v[134:135], v[134:135], 0.5, v[180:181] op_sel_hi:[1,0,1]
	v_and_b32_e32 v181, 0x7fffffff, v129
	v_and_b32_e32 v180, 0x7fffffff, v128
	v_pk_fma_f32 v[198:199], v[180:181], s[6:7], 1.0 op_sel_hi:[1,0,0]
	v_exp_f32_e32 v203, v203
	v_rcp_f32_e32 v198, v198
	v_rcp_f32_e32 v199, v199
	s_nop 0
	v_pk_fma_f32 v[200:201], v[198:199], s[92:93], v[178:179] op_sel_hi:[1,0,0]
	s_nop 0
	v_pk_fma_f32 v[200:201], v[198:199], v[200:201], s[96:97] op_sel_hi:[1,1,0]
	s_nop 0
	v_pk_fma_f32 v[200:201], v[198:199], v[200:201], s[44:45] op_sel_hi:[1,1,0]
	s_nop 0
	v_pk_fma_f32 v[200:201], v[198:199], v[200:201], s[58:59] op_sel_hi:[1,1,0]
	s_nop 0
	v_pk_mul_f32 v[198:199], v[198:199], v[200:201]
	v_pk_mul_f32 v[200:201], v[130:131], v[130:131]
	v_pk_fma_f32 v[198:199], v[202:203], v[198:199], 0.5 op_sel_hi:[1,1,0] neg_lo:[1,0,0] neg_hi:[1,0,0]
	s_nop 0
	v_pk_mul_f32 v[180:181], v[180:181], v[198:199]
	s_nop 0
	v_pk_fma_f32 v[128:129], v[128:129], 0.5, v[180:181] op_sel_hi:[1,0,1]
	v_and_b32_e32 v181, 0x7fffffff, v131
	v_and_b32_e32 v180, 0x7fffffff, v130
	v_pk_fma_f32 v[198:199], v[180:181], s[6:7], 1.0 op_sel_hi:[1,0,0]
	s_nop 0
	v_rcp_f32_e32 v198, v198
	v_rcp_f32_e32 v199, v199
	s_nop 0
	v_pk_fma_f32 v[178:179], v[198:199], s[92:93], v[178:179] op_sel_hi:[1,0,0]
	s_nop 0
	v_pk_fma_f32 v[178:179], v[198:199], v[178:179], s[96:97] op_sel_hi:[1,1,0]
	s_nop 0
	v_pk_fma_f32 v[178:179], v[198:199], v[178:179], s[44:45] op_sel_hi:[1,1,0]
	s_nop 0
	v_pk_fma_f32 v[178:179], v[198:199], v[178:179], s[58:59] op_sel_hi:[1,1,0]
	s_nop 0
	v_pk_mul_f32 v[178:179], v[198:199], v[178:179]
	v_pk_mul_f32 v[198:199], v[200:201], s[60:61] op_sel_hi:[1,0]
	s_nop 0
	v_exp_f32_e32 v198, v198
	v_exp_f32_e32 v199, v199
	s_nop 0
	v_pk_fma_f32 v[178:179], v[198:199], v[178:179], 0.5 op_sel_hi:[1,1,0] neg_lo:[1,0,0] neg_hi:[1,0,0]
	s_nop 0
	v_pk_mul_f32 v[178:179], v[180:181], v[178:179]
	v_cvt_pk_bf16_f32 v180, v128, v129
	s_nop 0
	v_pk_fma_f32 v[130:131], v[130:131], 0.5, v[178:179] op_sel_hi:[1,0,1]
	v_cvt_pk_bf16_f32 v178, v132, v133
	v_cvt_pk_bf16_f32 v179, v134, v135
	s_nop 0
	v_cvt_pk_bf16_f32 v181, v130, v131
	global_store_dwordx4 v[176:177], v[178:181], off offset:256
	s_cbranch_scc1 .LBB0_124
	v_pk_mul_f32 v[202:203], v[134:135], v[134:135]
	v_mov_b32_e32 v206, v132
	v_mov_b32_e32 v207, v134
	v_mov_b32_e32 v134, v133
	v_mov_b32_e32 v180, v141
	v_mov_b32_e32 v181, v143
	v_pk_mul_f32 v[200:201], v[132:133], v[132:133]
	v_pk_add_f32 v[132:133], v[206:207], v[134:135]
	v_mov_b32_e32 v178, v140
	v_mov_b32_e32 v179, v142
	v_pk_mul_f32 v[180:181], v[180:181], v[180:181]
	v_pk_add_f32 v[132:133], v[132:133], v[132:133] op_sel:[0,1] op_sel_hi:[1,0]
	v_pk_fma_f32 v[178:179], v[178:179], v[178:179], v[180:181]
	v_pk_mul_f32 v[204:205], v[128:129], v[128:129]
	v_pk_add_f32 v[140:141], v[140:141], v[140:141] op_sel:[0,1] op_sel_hi:[1,0]
	v_pk_add_f32 v[142:143], v[142:143], v[142:143] op_sel:[0,1] op_sel_hi:[1,0]
	v_pk_add_f32 v[128:129], v[128:129], v[128:129] op_sel:[0,1] op_sel_hi:[1,0]
	v_and_b32_e32 v133, 64, v189
	v_pk_add_f32 v[178:179], v[178:179], v[178:179] op_sel_hi:[0,1]
	v_xor_b32_e32 v129, 16, v189
	v_add_u32_e32 v197, 64, v133
	v_mov_b32_e32 v141, v200
	v_mov_b32_e32 v143, v201
	v_pk_mul_f32 v[176:177], v[138:139], v[138:139]
	v_mul_f32_e32 v178, v136, v136
	v_cmp_lt_i32_e32 vcc, v129, v197
	v_mov_b32_e32 v134, v138
	v_mov_b32_e32 v135, v204
	v_mov_b32_e32 v204, v139
	v_pk_add_f32 v[138:139], v[140:141], v[142:143]
	v_mov_b32_e32 v140, v136
	v_mov_b32_e32 v141, v202
	v_mov_b32_e32 v202, v137
	v_pk_fma_f32 v[180:181], v[136:137], v[136:137], v[178:179] op_sel_hi:[1,1,0]
	v_mul_f32_e32 v178, v130, v130
	v_cndmask_b32_e32 v129, v189, v129, vcc
	v_pk_add_f32 v[136:137], v[140:141], v[202:203]
	v_pk_fma_f32 v[198:199], v[130:131], v[130:131], v[178:179] op_sel_hi:[1,1,0]
	v_lshlrev_b32_e32 v206, 2, v129
	v_pk_add_f32 v[134:135], v[134:135], v[204:205]
	v_pk_add_f32 v[136:137], v[138:139], v[136:137]
	v_mov_b32_e32 v178, v130
	v_mov_b32_e32 v180, v131
	v_mov_b32_e32 v133, v176
	v_mov_b32_e32 v129, v177
	v_pk_add_f32 v[134:135], v[136:137], v[134:135]
	v_mov_b32_e32 v198, v145
	v_pk_add_f32 v[130:131], v[178:179], v[180:181]
	v_pk_add_f32 v[128:129], v[132:133], v[128:129]
	v_pk_add_f32 v[134:135], v[134:135], v[198:199]
	v_pk_add_f32 v[128:129], v[128:129], v[130:131]
	v_xor_b32_e32 v132, 32, v189
	v_pk_add_f32 v[128:129], v[128:129], v[134:135]
	ds_bpermute_b32 v130, v206, v128
	ds_bpermute_b32 v131, v206, v129
	v_cmp_lt_i32_e32 vcc, v132, v197
	s_waitcnt lgkmcnt(0)
	v_pk_add_f32 v[128:129], v[128:129], v[130:131]
	v_cndmask_b32_e32 v132, v189, v132, vcc
	v_lshlrev_b32_e32 v132, 2, v132
	ds_bpermute_b32 v130, v132, v128
	ds_bpermute_b32 v131, v132, v129
	s_and_saveexec_b64 s[6:7], s[0:1]
	s_cbranch_execz .LBB0_123
	v_lshlrev_b64 v[132:133], 8, v[174:175]
	s_waitcnt lgkmcnt(0)
	v_pk_add_f32 v[128:129], v[128:129], v[130:131]
	v_lshl_add_u64 v[130:131], s[16:17], 0, v[132:133]
	v_lshl_add_u64 v[130:131], s[26:27], 3, v[130:131]
	global_store_dwordx2 v[130:131], v[128:129], off

	.amdhsa_kernel _Z4mega6Params
		.amdhsa_group_segment_fixed_size 0
		.amdhsa_private_segment_fixed_size 0
		.amdhsa_kernarg_size 432
		.amdhsa_user_sgpr_count 2
		.amdhsa_user_sgpr_dispatch_ptr 0
		.amdhsa_user_sgpr_queue_ptr 0
		.amdhsa_user_sgpr_kernarg_segment_ptr 1
		.amdhsa_user_sgpr_dispatch_id 0
		.amdhsa_user_sgpr_kernarg_preload_length 0
		.amdhsa_user_sgpr_kernarg_preload_offset 0
		.amdhsa_user_sgpr_private_segment_size 0
		.amdhsa_uses_dynamic_stack 0
		.amdhsa_enable_private_segment 0
		.amdhsa_system_sgpr_workgroup_id_x 1
		.amdhsa_system_sgpr_workgroup_id_y 0
		.amdhsa_system_sgpr_workgroup_id_z 0
		.amdhsa_system_sgpr_workgroup_info 0
		.amdhsa_system_vgpr_workitem_id 2
		.amdhsa_next_free_vgpr 250
		.amdhsa_next_free_sgpr 102
		.amdhsa_accum_offset 252
		.amdhsa_reserve_vcc 1
		.amdhsa_float_round_mode_32 0
		.amdhsa_float_round_mode_16_64 0
		.amdhsa_float_denorm_mode_32 3
		.amdhsa_float_denorm_mode_16_64 3
		.amdhsa_dx10_clamp 1
		.amdhsa_ieee_mode 1
		.amdhsa_fp16_overflow 0
		.amdhsa_tg_split 0
		.amdhsa_exception_fp_ieee_invalid_op 0
		.amdhsa_exception_fp_denorm_src 0
		.amdhsa_exception_fp_ieee_div_zero 0
		.amdhsa_exception_fp_ieee_overflow 0
		.amdhsa_exception_fp_ieee_underflow 0
		.amdhsa_exception_fp_ieee_inexact 0
		.amdhsa_exception_int_div_zero 0
	.end_amdhsa_kernel

amdhsa.kernels:
  - .agpr_count:     0
    .args:
      - .offset:         0
        .size:           176
        .value_kind:     by_value
      - .offset:         176
        .size:           4
        .value_kind:     hidden_block_count_x
      - .offset:         180
        .size:           4
        .value_kind:     hidden_block_count_y
      - .offset:         184
        .size:           4
        .value_kind:     hidden_block_count_z
      - .offset:         188
        .size:           2
        .value_kind:     hidden_group_size_x
      - .offset:         190
        .size:           2
        .value_kind:     hidden_group_size_y
      - .offset:         192
        .size:           2
        .value_kind:     hidden_group_size_z
      - .offset:         194
        .size:           2
        .value_kind:     hidden_remainder_x
      - .offset:         196
        .size:           2
        .value_kind:     hidden_remainder_y
      - .offset:         198
        .size:           2
        .value_kind:     hidden_remainder_z
      - .offset:         216
        .size:           8
        .value_kind:     hidden_global_offset_x
      - .offset:         224
        .size:           8
        .value_kind:     hidden_global_offset_y
      - .offset:         232
        .size:           8
        .value_kind:     hidden_global_offset_z
      - .offset:         240
        .size:           2
        .value_kind:     hidden_grid_dims
      - .offset:         264
        .size:           8
        .value_kind:     hidden_multigrid_sync_arg
      - .offset:         296
        .size:           4
        .value_kind:     hidden_dynamic_lds_size
    .group_segment_fixed_size: 0
    .kernarg_segment_align: 8
    .kernarg_segment_size: 432
    .language:       OpenCL C
    .language_version:
      - 2
      - 0
    .max_flat_workgroup_size: 512
    .name:           _Z4mega6Params
    .private_segment_fixed_size: 0
    .sgpr_count:     108
    .sgpr_spill_count: 95
    .symbol:         _Z4mega6Params.kd
    .uniform_work_group_size: 1
    .uses_dynamic_stack: false
    .vgpr_count:     250
    .vgpr_spill_count: 0
    .wavefront_size: 64
